# attention: one static s_setprio 1 for waves 4-7 for the whole phase, per-segment setprio flips removed (on top of hand-written P1/P6 + P4 epilogue hoist)
# speedup vs baseline: 1.0062x; 1.0062x over previous
; #define ABAR() do { asm volatile("s_waitcnt lgkmcnt(0)" ::: "memory"); __builtin_amdgcn_s_barrier(); asm volatile("" ::: "memory"); } while (0)
; #define VWAIT() asm volatile("s_waitcnt vmcnt(0)" ::: "memory")
; #define DMA_TK(t_) do { const int ui_ = (t_) / NT, j_ = (t_) - ui_ * NT, un_ = vcu + ui_ * G; DMA_K(j_, (un_ >> 7), ((un_ >> 3) & 15), ((t_) % 3)); } while (0)
; #define DMA_TV(t_) do { const int ui_ = (t_) / NT, j_ = (t_) - ui_ * NT, un_ = vcu + ui_ * G; DMA_V(j_, (un_ >> 7), ((un_ >> 3) & 15), ((t_) % 3)); } while (0)
; __device__ __forceinline__ void attn_phase(const bf16_t* __restrict__ Q, const bf16_t* __restrict__ KN, const bf16_t* __restrict__ KR, const bf16_t* __restrict__ V, ...
;     ...
;   if (T > 0) {
;     float m_reg = -1e30f, l_reg = 0, mn, al; f32x16 o[4] = {}; bf16x8 qr[NQREG]; f32x16 p0, p1; bf16x8 pa0, pa1, pa2, pa3; u32x4 gv[2][4];
;     if (half == 1) { DMA_TK(0); DMA_TK(1); } else { DMA_TV(0); DMA_TV(1); }
;     LOADQ(vcu);
;     VWAIT(); __syncthreads();
;     if (half == 1) ABAR();
.LBB0_1083:
	s_cmpk_lt_u32 s35, 0x100
	s_cbranch_scc1 .Lattn_prio_done
	s_setprio 1

; #define SBAR() __builtin_amdgcn_sched_barrier(0)
; #define KLD(d) do { k0[(d) % 4] = *reinterpret_cast<const bf16x8*>(kb + (d) * 512); k1[(d) % 4] = *reinterpret_cast<const bf16x8*>(kb + 12288 + (d) * 512); } while (0)
; #define KLD(d) do { k0[(d) % 4] = *reinterpret_cast<const bf16x8*>(kb + (d) * 512); k1[(d) % 4] = *reinterpret_cast<const bf16x8*>(kb + 12288 + (d) * 512); } while (0)
; __device__ __forceinline__ void qkt(f32x16& p0, f32x16& p1, const char* Ks, const bf16x8* qr, const char* Qr, int kbase) {
;   p0 = f32x16{}; p1 = f32x16{};
;   const char* kb = Ks + kbase;
;   bf16x8 k0[4], k1[4];
;     ...
;   KLD(0); KLD(1); KLD(2);
;   __builtin_amdgcn_s_setprio(1);
; #pragma unroll
;   for (int d0 = 0; d0 < 12; ++d0) {
;     if (d0 + 3 < 12) KLD(d0 + 3);
;     const bf16x8 qf = d0 < NQREG ? qr[d0 < NQREG ? d0 : 0] : *reinterpret_cast<const bf16x8*>(Qr + (d0 - NQREG) * 8192);
;     p0 = __builtin_amdgcn_mfma_f32_32x32x16_bf16(k0[d0 % 4], qf, p0, 0, 0, 0);
;     p1 = __builtin_amdgcn_mfma_f32_32x32x16_bf16(k1[d0 % 4], qf, p1, 0, 0, 0);
;     SBAR(); }
;   __builtin_amdgcn_s_setprio(0);
;     ...
; }
.LBB0_1094:
	s_mul_i32 s4, s40, 0x6000
	v_add_u32_e32 v33, s4, v211
	ds_read_b128 v[34:37], v33
	ds_read_b128 v[38:41], v33 offset:512
	ds_read_b128 v[42:45], v33 offset:12288
	ds_read_b128 v[214:217], v33 offset:1024
	ds_read_b128 v[218:221], v33 offset:12800
	ds_read_b128 v[222:225], v33 offset:13312
	s_waitcnt vmcnt(0) lgkmcnt(0)
	v_mfma_f32_32x32x16_bf16 v[96:111], v[34:37], v[112:115], 0
	ds_read_b128 v[34:37], v33 offset:1536
	ds_read_b128 v[226:229], v33 offset:13824
	s_waitcnt lgkmcnt(5)
	v_mfma_f32_32x32x16_bf16 v[80:95], v[42:45], v[112:115], 0
	v_mfma_f32_32x32x16_bf16 v[96:111], v[38:41], v[116:119], v[96:111]
	ds_read_b128 v[38:41], v33 offset:2048
	ds_read_b128 v[42:45], v33 offset:14336
	s_waitcnt lgkmcnt(5)
	v_mfma_f32_32x32x16_bf16 v[80:95], v[218:221], v[116:119], v[80:95]
	v_mfma_f32_32x32x16_bf16 v[96:111], v[214:217], v[120:123], v[96:111]
	ds_read_b128 v[214:217], v33 offset:2560
	ds_read_b128 v[218:221], v33 offset:14848
	s_waitcnt lgkmcnt(6)
	v_mfma_f32_32x32x16_bf16 v[80:95], v[222:225], v[120:123], v[80:95]
	s_waitcnt lgkmcnt(5)
	v_mfma_f32_32x32x16_bf16 v[96:111], v[34:37], v[124:127], v[96:111]
	ds_read_b128 v[34:37], v33 offset:3072
	ds_read_b128 v[222:225], v33 offset:15360
	s_waitcnt lgkmcnt(6)
	v_mfma_f32_32x32x16_bf16 v[80:95], v[226:229], v[124:127], v[80:95]
	s_waitcnt lgkmcnt(5)
	v_mfma_f32_32x32x16_bf16 v[96:111], v[38:41], v[128:131], v[96:111]
	ds_read_b128 v[38:41], v33 offset:3584
	ds_read_b128 v[226:229], v33 offset:15872
	s_waitcnt lgkmcnt(6)
	v_mfma_f32_32x32x16_bf16 v[80:95], v[42:45], v[128:131], v[80:95]
	s_waitcnt lgkmcnt(5)
	v_mfma_f32_32x32x16_bf16 v[96:111], v[214:217], v[132:135], v[96:111]
	ds_read_b128 v[42:45], v33 offset:4096
	ds_read_b128 v[214:217], v33 offset:16384
	s_waitcnt lgkmcnt(6)
	v_mfma_f32_32x32x16_bf16 v[80:95], v[218:221], v[132:135], v[80:95]
	s_waitcnt lgkmcnt(5)
	v_mfma_f32_32x32x16_bf16 v[96:111], v[34:37], v[136:139], v[96:111]
	ds_read_b128 v[34:37], v33 offset:4608
	ds_read_b128 v[218:221], v33 offset:16896
	s_waitcnt lgkmcnt(6)
	v_mfma_f32_32x32x16_bf16 v[80:95], v[222:225], v[136:139], v[80:95]
	s_waitcnt lgkmcnt(5)
	v_mfma_f32_32x32x16_bf16 v[96:111], v[38:41], v[140:143], v[96:111]
	ds_read_b128 v[38:41], v33 offset:5120
	ds_read_b128 v[222:225], v33 offset:17408
	s_waitcnt lgkmcnt(6)
	v_mfma_f32_32x32x16_bf16 v[80:95], v[226:229], v[140:143], v[80:95]
	s_waitcnt lgkmcnt(5)
	v_mfma_f32_32x32x16_bf16 v[96:111], v[42:45], v[144:147], v[96:111]
	ds_read_b128 v[42:45], v33 offset:5632
	ds_read_b128 v[226:229], v33 offset:17920
	s_waitcnt lgkmcnt(6)
	v_mfma_f32_32x32x16_bf16 v[80:95], v[214:217], v[144:147], v[80:95]
	s_waitcnt lgkmcnt(5)
	v_mfma_f32_32x32x16_bf16 v[96:111], v[34:37], v[148:151], v[96:111]
	s_waitcnt lgkmcnt(4)
	v_mfma_f32_32x32x16_bf16 v[80:95], v[218:221], v[148:151], v[80:95]
	s_waitcnt lgkmcnt(3)
	v_mfma_f32_32x32x16_bf16 v[96:111], v[38:41], v[152:155], v[96:111]
	s_waitcnt lgkmcnt(2)
	v_mfma_f32_32x32x16_bf16 v[80:95], v[222:225], v[152:155], v[80:95]
	s_waitcnt lgkmcnt(1)
	v_mfma_f32_32x32x16_bf16 v[96:111], v[42:45], v[156:159], v[96:111]
	s_waitcnt lgkmcnt(0)
	v_mfma_f32_32x32x16_bf16 v[80:95], v[226:229], v[156:159], v[80:95]
	s_and_b64 vcc, exec, s[8:9]
	s_cbranch_vccnz .LBB0_1096
	s_waitcnt vmcnt(0)

; #define SBAR() __builtin_amdgcn_sched_barrier(0)
; #define KLD(d) do { k0[(d) % 4] = *reinterpret_cast<const bf16x8*>(kb + (d) * 512); k1[(d) % 4] = *reinterpret_cast<const bf16x8*>(kb + 12288 + (d) * 512); } while (0)
; #define KLD(d) do { k0[(d) % 4] = *reinterpret_cast<const bf16x8*>(kb + (d) * 512); k1[(d) % 4] = *reinterpret_cast<const bf16x8*>(kb + 12288 + (d) * 512); } while (0)
; __device__ __forceinline__ void qkt_pv(f32x16& p0, f32x16& p1, const char* Ks, const bf16x8* qr, const char* Qr, int kbase, f32x16* o, int vb, bf16x8 pa0, bf16x8 pa1, bf16x8 pa2, bf16x8 pa3) {
;   p0 = f32x16{}; p1 = f32x16{};
;   const char* kb = Ks + kbase;
;   bf16x8 k0[4], k1[4]; VFrag fa, fb;
;     ...
;   KLD(0); KLD(1); KLD(2);
;   __builtin_amdgcn_s_setprio(1);
; #pragma unroll
;   for (int d0 = 0; d0 < 12; ++d0) {
;     if (d0 + 3 < 12) KLD(d0 + 3);
;     if (d0 == 10) v_read8<0>(fa, vb);
;     const bf16x8 qf = d0 < NQREG ? qr[d0 < NQREG ? d0 : 0] : *reinterpret_cast<const bf16x8*>(Qr + (d0 - NQREG) * 8192);
;     p0 = __builtin_amdgcn_mfma_f32_32x32x16_bf16(k0[d0 % 4], qf, p0, 0, 0, 0);
;     p1 = __builtin_amdgcn_mfma_f32_32x32x16_bf16(k1[d0 % 4], qf, p1, 0, 0, 0);
;     SBAR(); }
;     ...
;   v_read8<1>(fb, vb);
;   asm volatile("s_waitcnt lgkmcnt(8)" ::: "memory"); SBAR(); pv_mma(o[0], fa, pa0, pa1, pa2, pa3); SBAR();
;   v_read8<2>(fa, vb);
;   asm volatile("s_waitcnt lgkmcnt(8)" ::: "memory"); SBAR(); pv_mma(o[1], fb, pa0, pa1, pa2, pa3); SBAR();
;   v_read8<3>(fb, vb);
;   asm volatile("s_waitcnt lgkmcnt(8)" ::: "memory"); SBAR(); pv_mma(o[2], fa, pa0, pa1, pa2, pa3); SBAR();
;   asm volatile("s_waitcnt lgkmcnt(0)" ::: "memory"); SBAR(); pv_mma(o[3], fb, pa0, pa1, pa2, pa3); SBAR();
;   __builtin_amdgcn_s_setprio(0);
; }
.LBB0_1113:
	s_mov_b32 s6, s40
	s_mov_b32 s40, s72
	s_mul_i32 s7, s72, 0x6000
	v_add_u32_e32 v46, s7, v211
	ds_read_b128 v[80:83], v46
	ds_read_b128 v[214:217], v46 offset:512
	ds_read_b128 v[84:87], v46 offset:12288
	ds_read_b128 v[218:221], v46 offset:1024
	ds_read_b128 v[222:225], v46 offset:12800
	ds_read_b128 v[226:229], v46 offset:13312
	v_lshl_add_u32 v187, s6, 14, v209
	s_waitcnt lgkmcnt(0)
	v_mfma_f32_32x32x16_bf16 v[96:111], v[80:83], v[112:115], 0
	ds_read_b128 v[230:233], v46 offset:1536
	ds_read_b128 v[234:237], v46 offset:13824
	v_mfma_f32_32x32x16_bf16 v[80:95], v[84:87], v[112:115], 0
	v_mfma_f32_32x32x16_bf16 v[96:111], v[214:217], v[116:119], v[96:111]
	ds_read_b128 v[214:217], v46 offset:2048
	ds_read_b128 v[238:241], v46 offset:14336
	v_mfma_f32_32x32x16_bf16 v[80:95], v[222:225], v[116:119], v[80:95]
	v_mfma_f32_32x32x16_bf16 v[96:111], v[218:221], v[120:123], v[96:111]
	ds_read_b128 v[218:221], v46 offset:2560
	ds_read_b128 v[222:225], v46 offset:14848
	v_mfma_f32_32x32x16_bf16 v[80:95], v[226:229], v[120:123], v[80:95]
	s_waitcnt lgkmcnt(0)
	v_mfma_f32_32x32x16_bf16 v[96:111], v[230:233], v[124:127], v[96:111]
	ds_read_b128 v[226:229], v46 offset:3072
	ds_read_b128 v[230:233], v46 offset:15360
	v_mfma_f32_32x32x16_bf16 v[80:95], v[234:237], v[124:127], v[80:95]
	v_mfma_f32_32x32x16_bf16 v[96:111], v[214:217], v[128:131], v[96:111]
	ds_read_b128 v[214:217], v46 offset:3584
	ds_read_b128 v[234:237], v46 offset:15872
	v_mfma_f32_32x32x16_bf16 v[80:95], v[238:241], v[128:131], v[80:95]
	v_mfma_f32_32x32x16_bf16 v[96:111], v[218:221], v[132:135], v[96:111]
	ds_read_b128 v[218:221], v46 offset:4096
	ds_read_b128 v[238:241], v46 offset:16384
	v_mfma_f32_32x32x16_bf16 v[80:95], v[222:225], v[132:135], v[80:95]
	s_waitcnt lgkmcnt(0)
	v_mfma_f32_32x32x16_bf16 v[96:111], v[226:229], v[136:139], v[96:111]
	ds_read_b128 v[222:225], v46 offset:4608
	ds_read_b128 v[226:229], v46 offset:16896
	v_mfma_f32_32x32x16_bf16 v[80:95], v[230:233], v[136:139], v[80:95]
	v_mfma_f32_32x32x16_bf16 v[96:111], v[214:217], v[140:143], v[96:111]
	ds_read_b128 v[214:217], v46 offset:5120
	ds_read_b128 v[230:233], v46 offset:17408
	v_mfma_f32_32x32x16_bf16 v[80:95], v[234:237], v[140:143], v[80:95]
	v_mfma_f32_32x32x16_bf16 v[96:111], v[218:221], v[144:147], v[96:111]
	ds_read_b128 v[218:221], v46 offset:5632
	ds_read_b128 v[234:237], v46 offset:17920
	v_mfma_f32_32x32x16_bf16 v[80:95], v[238:241], v[144:147], v[80:95]
	s_waitcnt lgkmcnt(0)
	v_mfma_f32_32x32x16_bf16 v[96:111], v[222:225], v[148:151], v[96:111]
	v_mfma_f32_32x32x16_bf16 v[80:95], v[226:229], v[148:151], v[80:95]
	ds_read_b64_tr_b16 v[222:223], v187 offset:0
	ds_read_b64_tr_b16 v[224:225], v187 offset:0x800
	v_mfma_f32_32x32x16_bf16 v[96:111], v[214:217], v[152:155], v[96:111]
	ds_read_b64_tr_b16 v[214:215], v187 offset:0x1000
	ds_read_b64_tr_b16 v[216:217], v187 offset:0x1800
	ds_read_b64_tr_b16 v[226:227], v187 offset:0x2000
	ds_read_b64_tr_b16 v[228:229], v187 offset:0x2800
	ds_read_b64_tr_b16 v[238:239], v187 offset:0x3000
	ds_read_b64_tr_b16 v[240:241], v187 offset:0x3800
	v_mfma_f32_32x32x16_bf16 v[80:95], v[230:233], v[152:155], v[80:95]
	v_mfma_f32_32x32x16_bf16 v[96:111], v[218:221], v[156:159], v[96:111]
	v_mfma_f32_32x32x16_bf16 v[80:95], v[234:237], v[156:159], v[80:95]
	ds_read_b64_tr_b16 v[218:219], v187 offset:0x200
	ds_read_b64_tr_b16 v[220:221], v187 offset:0xa00
	ds_read_b64_tr_b16 v[230:231], v187 offset:0x1200
	ds_read_b64_tr_b16 v[232:233], v187 offset:0x1a00
	ds_read_b64_tr_b16 v[234:235], v187 offset:0x2200
	ds_read_b64_tr_b16 v[236:237], v187 offset:0x2a00
	ds_read_b64_tr_b16 v[242:243], v187 offset:0x3200
	ds_read_b64_tr_b16 v[244:245], v187 offset:0x3a00
	s_waitcnt lgkmcnt(8)
	v_mfma_f32_32x32x16_bf16 v[64:79], v[34:37], v[222:225], v[64:79]
	v_mfma_f32_32x32x16_bf16 v[64:79], v[38:41], v[214:217], v[64:79]
	v_mfma_f32_32x32x16_bf16 v[64:79], v[42:45], v[226:229], v[64:79]
	v_mfma_f32_32x32x16_bf16 v[64:79], v[160:163], v[238:241], v[64:79]
	ds_read_b64_tr_b16 v[214:215], v187 offset:0x400
	ds_read_b64_tr_b16 v[216:217], v187 offset:0xc00
	ds_read_b64_tr_b16 v[222:223], v187 offset:0x1400
	ds_read_b64_tr_b16 v[224:225], v187 offset:0x1c00
	ds_read_b64_tr_b16 v[226:227], v187 offset:0x2400
	ds_read_b64_tr_b16 v[228:229], v187 offset:0x2c00
	ds_read_b64_tr_b16 v[238:239], v187 offset:0x3400
	ds_read_b64_tr_b16 v[240:241], v187 offset:0x3c00
	s_waitcnt lgkmcnt(8)
	v_mfma_f32_32x32x16_bf16 v[48:63], v[34:37], v[218:221], v[48:63]
	v_mfma_f32_32x32x16_bf16 v[48:63], v[38:41], v[230:233], v[48:63]
	v_mfma_f32_32x32x16_bf16 v[48:63], v[42:45], v[234:237], v[48:63]
	v_mfma_f32_32x32x16_bf16 v[48:63], v[160:163], v[242:245], v[48:63]
	ds_read_b64_tr_b16 v[218:219], v187 offset:0x600
	ds_read_b64_tr_b16 v[220:221], v187 offset:0xe00
	ds_read_b64_tr_b16 v[230:231], v187 offset:0x1600
	ds_read_b64_tr_b16 v[232:233], v187 offset:0x1e00
	ds_read_b64_tr_b16 v[234:235], v187 offset:0x2600
	ds_read_b64_tr_b16 v[236:237], v187 offset:0x2e00
	ds_read_b64_tr_b16 v[242:243], v187 offset:0x3600
	ds_read_b64_tr_b16 v[244:245], v187 offset:0x3e00
	s_waitcnt lgkmcnt(8)
	v_mfma_f32_32x32x16_bf16 v[16:31], v[34:37], v[214:217], v[16:31]
	v_mfma_f32_32x32x16_bf16 v[16:31], v[38:41], v[222:225], v[16:31]
	v_mfma_f32_32x32x16_bf16 v[16:31], v[42:45], v[226:229], v[16:31]
	v_mfma_f32_32x32x16_bf16 v[16:31], v[160:163], v[238:241], v[16:31]
	s_waitcnt lgkmcnt(0)
	v_mfma_f32_32x32x16_bf16 v[0:15], v[34:37], v[218:221], v[0:15]
	v_mfma_f32_32x32x16_bf16 v[0:15], v[38:41], v[230:233], v[0:15]
	v_mfma_f32_32x32x16_bf16 v[0:15], v[42:45], v[234:237], v[0:15]
	v_mfma_f32_32x32x16_bf16 v[0:15], v[160:163], v[242:245], v[0:15]
	s_and_b64 vcc, exec, s[8:9]
	s_cbranch_vccnz .LBB0_1115
	s_waitcnt vmcnt(0)

; #define SBAR() __builtin_amdgcn_sched_barrier(0)
; #define KLD(d) do { k0[(d) % 4] = *reinterpret_cast<const bf16x8*>(kb + (d) * 512); k1[(d) % 4] = *reinterpret_cast<const bf16x8*>(kb + 12288 + (d) * 512); } while (0)
; #define KLD(d) do { k0[(d) % 4] = *reinterpret_cast<const bf16x8*>(kb + (d) * 512); k1[(d) % 4] = *reinterpret_cast<const bf16x8*>(kb + 12288 + (d) * 512); } while (0)
; __device__ __forceinline__ void qkt_pv(f32x16& p0, f32x16& p1, const char* Ks, const bf16x8* qr, const char* Qr, int kbase, f32x16* o, int vb, bf16x8 pa0, bf16x8 pa1, bf16x8 pa2, bf16x8 pa3) {
;   p0 = f32x16{}; p1 = f32x16{};
;   const char* kb = Ks + kbase;
;   bf16x8 k0[4], k1[4]; VFrag fa, fb;
;     ...
;   KLD(0); KLD(1); KLD(2);
;   __builtin_amdgcn_s_setprio(1);
; #pragma unroll
;   for (int d0 = 0; d0 < 12; ++d0) {
;     if (d0 + 3 < 12) KLD(d0 + 3);
;     if (d0 == 10) v_read8<0>(fa, vb);
;     const bf16x8 qf = d0 < NQREG ? qr[d0 < NQREG ? d0 : 0] : *reinterpret_cast<const bf16x8*>(Qr + (d0 - NQREG) * 8192);
;     p0 = __builtin_amdgcn_mfma_f32_32x32x16_bf16(k0[d0 % 4], qf, p0, 0, 0, 0);
;     p1 = __builtin_amdgcn_mfma_f32_32x32x16_bf16(k1[d0 % 4], qf, p1, 0, 0, 0);
;     SBAR(); }
;     ...
;   v_read8<1>(fb, vb);
;   asm volatile("s_waitcnt lgkmcnt(8)" ::: "memory"); SBAR(); pv_mma(o[0], fa, pa0, pa1, pa2, pa3); SBAR();
;   v_read8<2>(fa, vb);
;   asm volatile("s_waitcnt lgkmcnt(8)" ::: "memory"); SBAR(); pv_mma(o[1], fb, pa0, pa1, pa2, pa3); SBAR();
;   v_read8<3>(fb, vb);
;   asm volatile("s_waitcnt lgkmcnt(8)" ::: "memory"); SBAR(); pv_mma(o[2], fa, pa0, pa1, pa2, pa3); SBAR();
;   asm volatile("s_waitcnt lgkmcnt(0)" ::: "memory"); SBAR(); pv_mma(o[3], fb, pa0, pa1, pa2, pa3); SBAR();
;   __builtin_amdgcn_s_setprio(0);
; }
.LBB0_1133:
	s_add_i32 s70, s70, 1
	s_cmp_ge_i32 s70, s47
	s_cselect_b64 s[6:7], -1, 0
	s_mul_i32 s30, s72, 0x6000
	v_add_u32_e32 v47, s30, v211
	ds_read_b128 v[80:83], v47
	ds_read_b128 v[214:217], v47 offset:512
	ds_read_b128 v[84:87], v47 offset:12288
	ds_read_b128 v[218:221], v47 offset:1024
	ds_read_b128 v[222:225], v47 offset:12800
	ds_read_b128 v[226:229], v47 offset:13312
	v_lshl_add_u32 v187, s40, 14, v209
	s_waitcnt lgkmcnt(0)
	v_mfma_f32_32x32x16_bf16 v[96:111], v[80:83], v[112:115], 0
	ds_read_b128 v[230:233], v47 offset:1536
	ds_read_b128 v[234:237], v47 offset:13824
	v_mfma_f32_32x32x16_bf16 v[80:95], v[84:87], v[112:115], 0
	v_mfma_f32_32x32x16_bf16 v[96:111], v[214:217], v[116:119], v[96:111]
	ds_read_b128 v[214:217], v47 offset:2048
	ds_read_b128 v[238:241], v47 offset:14336
	v_mfma_f32_32x32x16_bf16 v[80:95], v[222:225], v[116:119], v[80:95]
	v_mfma_f32_32x32x16_bf16 v[96:111], v[218:221], v[120:123], v[96:111]
	ds_read_b128 v[218:221], v47 offset:2560
	ds_read_b128 v[222:225], v47 offset:14848
	v_mfma_f32_32x32x16_bf16 v[80:95], v[226:229], v[120:123], v[80:95]
	s_waitcnt lgkmcnt(0)
	v_mfma_f32_32x32x16_bf16 v[96:111], v[230:233], v[124:127], v[96:111]
	ds_read_b128 v[226:229], v47 offset:3072
	ds_read_b128 v[230:233], v47 offset:15360
	v_mfma_f32_32x32x16_bf16 v[80:95], v[234:237], v[124:127], v[80:95]
	v_mfma_f32_32x32x16_bf16 v[96:111], v[214:217], v[128:131], v[96:111]
	ds_read_b128 v[214:217], v47 offset:3584
	ds_read_b128 v[234:237], v47 offset:15872
	v_mfma_f32_32x32x16_bf16 v[80:95], v[238:241], v[128:131], v[80:95]
	v_mfma_f32_32x32x16_bf16 v[96:111], v[218:221], v[132:135], v[96:111]
	ds_read_b128 v[218:221], v47 offset:4096
	ds_read_b128 v[238:241], v47 offset:16384
	v_mfma_f32_32x32x16_bf16 v[80:95], v[222:225], v[132:135], v[80:95]
	s_waitcnt lgkmcnt(0)
	v_mfma_f32_32x32x16_bf16 v[96:111], v[226:229], v[136:139], v[96:111]
	ds_read_b128 v[222:225], v47 offset:4608
	ds_read_b128 v[226:229], v47 offset:16896
	v_mfma_f32_32x32x16_bf16 v[80:95], v[230:233], v[136:139], v[80:95]
	v_mfma_f32_32x32x16_bf16 v[96:111], v[214:217], v[140:143], v[96:111]
	ds_read_b128 v[214:217], v47 offset:5120
	ds_read_b128 v[230:233], v47 offset:17408
	v_mfma_f32_32x32x16_bf16 v[80:95], v[234:237], v[140:143], v[80:95]
	v_mfma_f32_32x32x16_bf16 v[96:111], v[218:221], v[144:147], v[96:111]
	ds_read_b128 v[218:221], v47 offset:5632
	ds_read_b128 v[234:237], v47 offset:17920
	v_mfma_f32_32x32x16_bf16 v[80:95], v[238:241], v[144:147], v[80:95]
	s_waitcnt lgkmcnt(0)
	v_mfma_f32_32x32x16_bf16 v[96:111], v[222:225], v[148:151], v[96:111]
	v_mfma_f32_32x32x16_bf16 v[80:95], v[226:229], v[148:151], v[80:95]
	ds_read_b64_tr_b16 v[222:223], v187 offset:0
	ds_read_b64_tr_b16 v[224:225], v187 offset:0x800
	v_mfma_f32_32x32x16_bf16 v[96:111], v[214:217], v[152:155], v[96:111]
	ds_read_b64_tr_b16 v[214:215], v187 offset:0x1000
	ds_read_b64_tr_b16 v[216:217], v187 offset:0x1800
	ds_read_b64_tr_b16 v[226:227], v187 offset:0x2000
	ds_read_b64_tr_b16 v[228:229], v187 offset:0x2800
	ds_read_b64_tr_b16 v[238:239], v187 offset:0x3000
	ds_read_b64_tr_b16 v[240:241], v187 offset:0x3800
	v_mfma_f32_32x32x16_bf16 v[80:95], v[230:233], v[152:155], v[80:95]
	v_mfma_f32_32x32x16_bf16 v[96:111], v[218:221], v[156:159], v[96:111]
	v_mfma_f32_32x32x16_bf16 v[80:95], v[234:237], v[156:159], v[80:95]
	ds_read_b64_tr_b16 v[218:219], v187 offset:0x200
	ds_read_b64_tr_b16 v[220:221], v187 offset:0xa00
	ds_read_b64_tr_b16 v[230:231], v187 offset:0x1200
	ds_read_b64_tr_b16 v[232:233], v187 offset:0x1a00
	ds_read_b64_tr_b16 v[234:235], v187 offset:0x2200
	ds_read_b64_tr_b16 v[236:237], v187 offset:0x2a00
	ds_read_b64_tr_b16 v[242:243], v187 offset:0x3200
	ds_read_b64_tr_b16 v[244:245], v187 offset:0x3a00
	s_waitcnt lgkmcnt(8)
	v_mfma_f32_32x32x16_bf16 v[64:79], v[34:37], v[222:225], v[64:79]
	v_mfma_f32_32x32x16_bf16 v[64:79], v[38:41], v[214:217], v[64:79]
	v_mfma_f32_32x32x16_bf16 v[64:79], v[42:45], v[226:229], v[64:79]
	v_mfma_f32_32x32x16_bf16 v[64:79], v[160:163], v[238:241], v[64:79]
	ds_read_b64_tr_b16 v[214:215], v187 offset:0x400
	ds_read_b64_tr_b16 v[216:217], v187 offset:0xc00
	ds_read_b64_tr_b16 v[222:223], v187 offset:0x1400
	ds_read_b64_tr_b16 v[224:225], v187 offset:0x1c00
	ds_read_b64_tr_b16 v[226:227], v187 offset:0x2400
	ds_read_b64_tr_b16 v[228:229], v187 offset:0x2c00
	ds_read_b64_tr_b16 v[238:239], v187 offset:0x3400
	ds_read_b64_tr_b16 v[240:241], v187 offset:0x3c00
	s_waitcnt lgkmcnt(8)
	v_mfma_f32_32x32x16_bf16 v[48:63], v[34:37], v[218:221], v[48:63]
	v_mfma_f32_32x32x16_bf16 v[48:63], v[38:41], v[230:233], v[48:63]
	v_mfma_f32_32x32x16_bf16 v[48:63], v[42:45], v[234:237], v[48:63]
	v_mfma_f32_32x32x16_bf16 v[48:63], v[160:163], v[242:245], v[48:63]
	ds_read_b64_tr_b16 v[218:219], v187 offset:0x600
	ds_read_b64_tr_b16 v[220:221], v187 offset:0xe00
	ds_read_b64_tr_b16 v[230:231], v187 offset:0x1600
	ds_read_b64_tr_b16 v[232:233], v187 offset:0x1e00
	ds_read_b64_tr_b16 v[234:235], v187 offset:0x2600
	ds_read_b64_tr_b16 v[236:237], v187 offset:0x2e00
	ds_read_b64_tr_b16 v[242:243], v187 offset:0x3600
	ds_read_b64_tr_b16 v[244:245], v187 offset:0x3e00
	s_waitcnt lgkmcnt(8)
	v_mfma_f32_32x32x16_bf16 v[16:31], v[34:37], v[214:217], v[16:31]
	v_mfma_f32_32x32x16_bf16 v[16:31], v[38:41], v[222:225], v[16:31]
	v_mfma_f32_32x32x16_bf16 v[16:31], v[42:45], v[226:229], v[16:31]
	v_mfma_f32_32x32x16_bf16 v[16:31], v[160:163], v[238:241], v[16:31]
	s_waitcnt lgkmcnt(0)
	v_mfma_f32_32x32x16_bf16 v[0:15], v[34:37], v[218:221], v[0:15]
	v_mfma_f32_32x32x16_bf16 v[0:15], v[38:41], v[230:233], v[0:15]
	v_mfma_f32_32x32x16_bf16 v[0:15], v[42:45], v[234:237], v[0:15]
	v_mfma_f32_32x32x16_bf16 v[0:15], v[160:163], v[242:245], v[0:15]
	s_and_b64 vcc, exec, s[6:7]
	s_cbranch_vccnz .LBB0_1135
	s_mul_i32 s30, s70, s63
	s_add_i32 s30, s30, s46
	s_bfe_u32 s34, s30, 0x40003
	s_lshl_b32 s31, s30, 4
	s_lshl_b32 s30, s30, 8
	s_and_b32 s31, s31, 0xfffff800
	s_and_b32 s30, s30, 0x700
	s_or_b32 s30, s31, s30
	v_add_u32_e32 v36, s30, v212
	v_mov_b64_e32 v[34:35], s[16:17]
	v_mad_i64_i32 v[34:35], s[30:31], v36, s49, v[34:35]
	s_mul_i32 s40, s34, 0x180
	v_lshl_add_u64 v[34:35], v[34:35], 0, s[40:41]
	v_mov_b32_e32 v187, v32
	v_lshl_add_u64 v[34:35], v[34:35], 0, v[186:187]
	global_load_dwordx4 v[112:115], v[34:35], off
	global_load_dwordx4 v[116:119], v[34:35], off offset:32
	global_load_dwordx4 v[120:123], v[34:35], off offset:64
	global_load_dwordx4 v[124:127], v[34:35], off offset:96
	global_load_dwordx4 v[128:131], v[34:35], off offset:128
	global_load_dwordx4 v[132:135], v[34:35], off offset:160
	global_load_dwordx4 v[136:139], v[34:35], off offset:192
	global_load_dwordx4 v[140:143], v[34:35], off offset:224
	global_load_dwordx4 v[144:147], v[34:35], off offset:256
	global_load_dwordx4 v[148:151], v[34:35], off offset:288
	global_load_dwordx4 v[152:155], v[34:35], off offset:320
	global_load_dwordx4 v[156:159], v[34:35], off offset:352

; __device__ __forceinline__ void attn_phase(const bf16_t* __restrict__ Q, const bf16_t* __restrict__ KN, const bf16_t* __restrict__ KR, const bf16_t* __restrict__ V, ...
;     ...
;   asm volatile("s_waitcnt vmcnt(0)" ::: "memory"); __syncthreads();
.LBB0_1162:
	s_setprio 0
	s_waitcnt vmcnt(0)
	s_waitcnt vmcnt(0) lgkmcnt(0)
	s_barrier
